# v33 plus dense loop identity cndmask/cmp mask round-trips removed
# baseline (speedup 1.0000x reference)
.LBB0_441:
	s_and_b32 s48, s33, 2
	s_add_i32 s4, s33, -1
	s_and_b32 s49, s4, 3
	s_mul_i32 s4, s48, 0x4800
	v_add_u32_e32 v168, s4, v184
	s_cmp_eq_u32 s33, 0
	ds_read_b128 v[164:167], v168 offset:96
	s_cselect_b64 s[6:7], -1, 0
	s_mulk_i32 s49, 0x4800
	s_and_b64 s[4:5], s[6:7], exec
	s_cselect_b32 s4, 0, s49
	v_add_u32_e32 v84, s4, v184
	v_exp_f32_e32 v64, v64
	v_exp_f32_e32 v65, v65
	s_nop 0
	v_add_f32_e32 v113, v65, v64
	v_cvt_pk_bf16_f32 v112, v64, v65
	ds_read_b128 v[186:189], v84 offset:9280
	ds_read_b128 v[190:193], v84 offset:9312
	ds_read_b128 v[194:197], v84 offset:13888
	ds_read_b128 v[198:201], v84 offset:13920
	v_mfma_f32_32x32x16_bf16 v[80:95], v[80:83], v[148:151], 0
	v_exp_f32_e32 v64, v66
	v_exp_f32_e32 v65, v67
	v_add_f32_e32 v66, v64, v113
	v_add_f32_e32 v66, v65, v66
	v_cvt_pk_bf16_f32 v113, v64, v65
	v_mfma_f32_32x32x16_bf16 v[80:95], v[108:111], v[152:155], v[80:95]
	v_exp_f32_e32 v64, v68
	v_exp_f32_e32 v65, v69
	v_add_f32_e32 v66, v64, v66
	v_cvt_pk_bf16_f32 v114, v64, v65
	v_add_f32_e32 v64, v65, v66
	v_mfma_f32_32x32x16_bf16 v[80:95], v[104:107], v[156:159], v[80:95]
	v_exp_f32_e32 v65, v70
	v_exp_f32_e32 v66, v71
	v_add_f32_e32 v64, v65, v64
	v_cvt_pk_bf16_f32 v115, v65, v66
	v_add_f32_e32 v64, v66, v64
	s_waitcnt lgkmcnt(4)
	v_mfma_f32_32x32x16_bf16 v[80:95], v[164:167], v[160:163], v[80:95]
	v_exp_f32_e32 v65, v72
	v_exp_f32_e32 v66, v73
	v_add_f32_e32 v64, v65, v64
	v_cvt_pk_bf16_f32 v104, v65, v66
	v_add_f32_e32 v64, v66, v64
	s_waitcnt lgkmcnt(0)
	v_mfma_f32_32x32x16_bf16 v[16:31], v[186:189], v[96:99], v[16:31]
	v_exp_f32_e32 v65, v74
	v_exp_f32_e32 v66, v75
	v_add_f32_e32 v64, v65, v64
	v_cvt_pk_bf16_f32 v105, v65, v66
	v_add_f32_e32 v64, v66, v64
	v_mfma_f32_32x32x16_bf16 v[16:31], v[190:193], v[100:103], v[16:31]
	v_exp_f32_e32 v65, v76
	v_exp_f32_e32 v66, v77
	v_add_f32_e32 v64, v65, v64
	v_cvt_pk_bf16_f32 v106, v65, v66
	v_add_f32_e32 v64, v66, v64
	v_mfma_f32_32x32x16_bf16 v[0:15], v[194:197], v[96:99], v[0:15]
	v_exp_f32_e32 v65, v78
	v_exp_f32_e32 v66, v79
	v_add_f32_e32 v64, v65, v64
	v_cvt_pk_bf16_f32 v107, v65, v66
	v_add_f32_e32 v185, v66, v64
	v_exp_f32_e32 v68, v80
	v_exp_f32_e32 v69, v81
	s_nop 0
	v_add_f32_e32 v80, v69, v68
	v_cvt_pk_bf16_f32 v96, v68, v69
	v_mfma_f32_32x32x16_bf16 v[0:15], v[198:201], v[100:103], v[0:15]
	ds_read_b128 v[64:67], v168 offset:4608
	ds_read_b128 v[164:167], v168 offset:4640
	ds_read_b128 v[108:111], v168 offset:4672
	v_cmp_ge_f32_e32 vcc, s62, v185
	s_mov_b64 s[8:9], -1
	s_mov_b64 s[4:5], -1
	s_and_saveexec_b64 s[10:11], vcc
	v_cmp_gt_f32_e32 vcc, s75, v185
	s_and_b64 s[4:5], s[6:7], vcc
	s_orn2_b64 s[4:5], s[4:5], exec
	s_or_b64 exec, exec, s[10:11]
	ds_read_b128 v[186:189], v168 offset:4704
	s_waitcnt lgkmcnt(1)
	v_mfma_f32_32x32x16_bf16 v[64:79], v[64:67], v[116:119], 0
	ds_read_b128 v[190:193], v168 offset:9216
	ds_read_b128 v[194:197], v168 offset:9248
	ds_read_b128 v[198:201], v168 offset:13824
	ds_read_b128 v[230:233], v168 offset:13856
	v_exp_f32_e32 v81, v82
	v_exp_f32_e32 v82, v83
	v_add_f32_e32 v80, v81, v80
	v_add_f32_e32 v80, v82, v80
	v_cvt_pk_bf16_f32 v97, v81, v82
	v_mfma_f32_32x32x16_bf16 v[64:79], v[164:167], v[120:123], v[64:79]
	v_exp_f32_e32 v81, v84
	v_exp_f32_e32 v82, v85
	v_add_f32_e32 v80, v81, v80
	v_cvt_pk_bf16_f32 v98, v81, v82
	v_add_f32_e32 v80, v82, v80
	v_mfma_f32_32x32x16_bf16 v[64:79], v[108:111], v[124:127], v[64:79]
	v_exp_f32_e32 v81, v86
	v_exp_f32_e32 v82, v87
	v_add_f32_e32 v80, v81, v80
	v_cvt_pk_bf16_f32 v99, v81, v82
	v_add_f32_e32 v80, v82, v80
	s_waitcnt lgkmcnt(4)
	v_mfma_f32_32x32x16_bf16 v[64:79], v[186:189], v[128:131], v[64:79]
	v_exp_f32_e32 v81, v88
	v_exp_f32_e32 v82, v89
	v_add_f32_e32 v80, v81, v80
	v_cvt_pk_bf16_f32 v100, v81, v82
	v_add_f32_e32 v80, v82, v80
	s_waitcnt lgkmcnt(0)
	v_mfma_f32_32x32x16_bf16 v[48:63], v[190:193], v[112:115], v[48:63]
	v_exp_f32_e32 v81, v90
	v_exp_f32_e32 v82, v91
	v_add_f32_e32 v80, v81, v80
	v_cvt_pk_bf16_f32 v101, v81, v82
	v_add_f32_e32 v80, v82, v80
	v_mfma_f32_32x32x16_bf16 v[48:63], v[194:197], v[104:107], v[48:63]
	v_exp_f32_e32 v81, v92
	v_exp_f32_e32 v82, v93
	v_add_f32_e32 v80, v81, v80
	v_cvt_pk_bf16_f32 v102, v81, v82
	v_add_f32_e32 v80, v82, v80
	v_mfma_f32_32x32x16_bf16 v[32:47], v[198:201], v[112:115], v[32:47]
	v_exp_f32_e32 v81, v94
	v_exp_f32_e32 v82, v95
	v_add_f32_e32 v80, v81, v80
	v_cvt_pk_bf16_f32 v103, v81, v82
	v_add_f32_e32 v164, v82, v80
	v_exp_f32_e32 v64, v64
	v_exp_f32_e32 v65, v65
	s_nop 0
	v_add_f32_e32 v165, v65, v64
	v_cvt_pk_bf16_f32 v186, v64, v65
	v_mfma_f32_32x32x16_bf16 v[32:47], v[230:233], v[104:107], v[32:47]
	ds_read_b128 v[80:83], v168 offset:4608
	ds_read_b128 v[112:115], v168 offset:4640
	ds_read_b128 v[108:111], v168 offset:4672
	v_cmp_ge_f32_e32 vcc, s62, v164
	s_and_saveexec_b64 s[10:11], vcc
	v_cmp_gt_f32_e32 vcc, s75, v164
	s_and_b64 s[6:7], s[6:7], vcc
	s_orn2_b64 s[8:9], s[6:7], exec
	s_or_b64 exec, exec, s[10:11]
	s_mov_b64 s[6:7], s[8:9]
	ds_read_b128 v[104:107], v168 offset:4704
	s_waitcnt lgkmcnt(1)
; #define LAS __attribute__((address_space(3)))
; template <int MODE, bool FAST> __device__ __forceinline__ bool attn_unit(LAS unsigned char* lds, const AttU& U, const int wv) {
;     ...
;     pb[1][0] = (bf16x8){0, 0, 0, 0, 0, 0, 0, 0}; pb[1][1] = pb[1][0];
;     ATT_QK(0, 0, 0);
;     bf16x8 kpre[NPRE > 0 ? NPRE : 1];
; #pragma unroll
;     for (int i_ = 0; i_ < NPRE; ++i_) kpre[i_] = *(LAS const bf16x8*)(lds + koff + i_ * 32);
	v_mfma_f32_32x32x16_bf16 v[80:95], v[80:83], v[148:151], 0
	ds_read_b128 v[190:193], v168 offset:9216
	ds_read_b128 v[194:197], v168 offset:9248
	ds_read_b128 v[198:201], v168 offset:13824
	ds_read_b128 v[230:233], v168 offset:13856
	v_exp_f32_e32 v64, v66
	v_exp_f32_e32 v65, v67
	v_add_f32_e32 v66, v64, v165
	v_add_f32_e32 v66, v65, v66
	v_cvt_pk_bf16_f32 v187, v64, v65
	v_mfma_f32_32x32x16_bf16 v[80:95], v[112:115], v[152:155], v[80:95]
	v_exp_f32_e32 v64, v68
	v_exp_f32_e32 v65, v69
	v_add_f32_e32 v66, v64, v66
	v_cvt_pk_bf16_f32 v188, v64, v65
	v_add_f32_e32 v64, v65, v66
	v_mfma_f32_32x32x16_bf16 v[80:95], v[108:111], v[156:159], v[80:95]
	v_exp_f32_e32 v65, v70
	v_exp_f32_e32 v66, v71
	v_add_f32_e32 v64, v65, v64
	v_cvt_pk_bf16_f32 v189, v65, v66
	v_add_f32_e32 v64, v66, v64
	s_waitcnt lgkmcnt(4)
	v_mfma_f32_32x32x16_bf16 v[80:95], v[104:107], v[160:163], v[80:95]
	v_exp_f32_e32 v65, v72
	v_exp_f32_e32 v66, v73
	v_add_f32_e32 v64, v65, v64
	v_cvt_pk_bf16_f32 v108, v65, v66
	v_add_f32_e32 v64, v66, v64
	s_waitcnt lgkmcnt(0)
	v_mfma_f32_32x32x16_bf16 v[16:31], v[190:193], v[96:99], v[16:31]
	v_exp_f32_e32 v65, v74
	v_exp_f32_e32 v66, v75
	v_add_f32_e32 v64, v65, v64
	v_cvt_pk_bf16_f32 v109, v65, v66
	v_add_f32_e32 v64, v66, v64
	v_mfma_f32_32x32x16_bf16 v[16:31], v[194:197], v[100:103], v[16:31]
	v_exp_f32_e32 v65, v76
	v_exp_f32_e32 v66, v77
	v_add_f32_e32 v64, v65, v64
	v_cvt_pk_bf16_f32 v110, v65, v66
	v_add_f32_e32 v64, v66, v64
	v_mfma_f32_32x32x16_bf16 v[0:15], v[198:201], v[96:99], v[0:15]
	v_exp_f32_e32 v65, v78
	v_exp_f32_e32 v66, v79
	v_add_f32_e32 v64, v65, v64
	v_cvt_pk_bf16_f32 v111, v65, v66
	v_add_f32_e32 v104, v66, v64
	v_exp_f32_e32 v68, v80
	v_exp_f32_e32 v69, v81
	s_nop 0
	v_add_f32_e32 v81, v69, v68
	v_cvt_pk_bf16_f32 v80, v68, v69
	v_mfma_f32_32x32x16_bf16 v[0:15], v[230:233], v[100:103], v[0:15]
	ds_read_b128 v[64:67], v168 offset:18432
	ds_read_b128 v[96:99], v168 offset:18464
	ds_read_b128 v[112:115], v168 offset:18496
	v_cmp_nge_f32_e64 s[8:9], s62, v104
	ds_read_b128 v[100:103], v168 offset:18528
	s_waitcnt lgkmcnt(1)
	v_mfma_f32_32x32x16_bf16 v[64:79], v[64:67], v[116:119], 0
	ds_read_b128 v[190:193], v168 offset:9280
	ds_read_b128 v[194:197], v168 offset:9312
	ds_read_b128 v[198:201], v168 offset:13888
	ds_read_b128 v[230:233], v168 offset:13920
	v_exp_f32_e32 v82, v82
	v_exp_f32_e32 v83, v83
	v_add_f32_e32 v81, v82, v81
	v_add_f32_e32 v105, v83, v81
	v_cvt_pk_bf16_f32 v81, v82, v83
	v_mfma_f32_32x32x16_bf16 v[64:79], v[96:99], v[120:123], v[64:79]
	v_exp_f32_e32 v82, v84
	v_exp_f32_e32 v83, v85
	v_add_f32_e32 v84, v82, v105
	v_cvt_pk_bf16_f32 v82, v82, v83
	v_add_f32_e32 v83, v83, v84
	v_mfma_f32_32x32x16_bf16 v[64:79], v[112:115], v[124:127], v[64:79]
	v_exp_f32_e32 v84, v86
	v_exp_f32_e32 v85, v87
	v_add_f32_e32 v86, v84, v83
	v_cvt_pk_bf16_f32 v83, v84, v85
	v_add_f32_e32 v84, v85, v86
	s_waitcnt lgkmcnt(4)
	v_mfma_f32_32x32x16_bf16 v[64:79], v[100:103], v[128:131], v[64:79]
	v_exp_f32_e32 v85, v88
	v_exp_f32_e32 v86, v89
	v_add_f32_e32 v87, v85, v84
	v_cvt_pk_bf16_f32 v84, v85, v86
	v_add_f32_e32 v85, v86, v87
	s_waitcnt lgkmcnt(0)
	v_mfma_f32_32x32x16_bf16 v[48:63], v[190:193], v[186:189], v[48:63]
	v_exp_f32_e32 v86, v90
	v_exp_f32_e32 v87, v91
	v_add_f32_e32 v88, v86, v85
	v_cvt_pk_bf16_f32 v85, v86, v87
	v_add_f32_e32 v86, v87, v88
	v_mfma_f32_32x32x16_bf16 v[48:63], v[194:197], v[108:111], v[48:63]
	v_exp_f32_e32 v87, v92
	v_exp_f32_e32 v88, v93
	v_add_f32_e32 v89, v87, v86
	v_cvt_pk_bf16_f32 v86, v87, v88
	v_add_f32_e32 v87, v88, v89
	v_mfma_f32_32x32x16_bf16 v[32:47], v[198:201], v[186:189], v[32:47]
	v_exp_f32_e32 v88, v94
	v_exp_f32_e32 v89, v95
	v_add_f32_e32 v90, v88, v87
	v_cvt_pk_bf16_f32 v87, v88, v89
	v_add_f32_e32 v105, v89, v90
	v_mfma_f32_32x32x16_bf16 v[32:47], v[230:233], v[108:111], v[32:47]
	ds_read_b128 v[96:99], v168 offset:18432
	ds_read_b128 v[92:95], v168 offset:18464
	ds_read_b128 v[88:91], v168 offset:18496
	v_cmp_nge_f32_e64 s[10:11], s62, v105
	s_waitcnt lgkmcnt(0)
	s_barrier
	s_cmpk_gt_u32 s33, 0xfc
	s_cbranch_scc1 .LBB0_447
	v_add_u32_e32 v100, s49, v173
	s_waitcnt vmcnt(1)
	ds_write_b128 v100, v[140:143]
	s_waitcnt vmcnt(0)
	ds_write_b128 v100, v[144:147] offset:9216
